# sse2 + sliver GEMM loops: scalar address bookkeeping between the last sliver MFMA and the closing barrier moved after the barrier (compute wave arrives earlier)
# speedup vs baseline: 1.0034x; 1.0034x over previous
; #define PG8_MMA(ai, bj, At, Bt) do { __builtin_amdgcn_s_setprio(1); _Pragma("unroll") for (int m = 0; m < 4; ++m) _Pragma("unroll") for (int n = 0; n < 2; ++n) _Pragma("unroll") for (int k = 0; k < 2; ++k) \
;         acc[ai][bj][m][n] = __builtin_amdgcn_mfma_f32_16x16x32_bf16(Bt[n][k], At[m][k], acc[ai][bj][m][n], 0, 0, 0); __builtin_amdgcn_s_setprio(0); } while (0)
; #define PG8_WAIT_V89() do { if constexpr (SLIVER) PG8_WAIT_V(9); else PG8_WAIT_V(8); } while (0)
; #define PG8_WAIT_L(n) asm volatile("s_waitcnt lgkmcnt(" #n ")" ::: "memory")
; #define PG8_BAR __builtin_amdgcn_s_barrier()
; #define PG8_SCHED __builtin_amdgcn_sched_barrier(0)
; template <class Epi, class Sched, bool ALIGN_EPI = false, bool SP2 = false, bool SLIVER = false>
; __device__ __forceinline__ void gemm_phase(PG8_LAS unsigned char* lds, const Gemm g, const Sched& S, const Epi& E) {
;     ...
;         for (int t = 0; t < nt; t += 2) {
;             const bool last = (t == nt - 2);
;             const char* a1 = cA + (size_t)(t + 1) * kstep;
;             const char* a2 = last ? nA : cA + (size_t)(t + 2) * kstep; const char* b2 = last ? nB : cB + (size_t)(t + 2) * kstep;
;     ...
;             PG8_WAIT_V89(); PG8_WAIT_L(0); PG8_BAR; PG8_MMA(1, 0, At, B0); PG8_MMA(1, 1, At, B1); PG8_MMA_S(); PG8_BAR; PG8_SCHED;
.LBB0_497:
	s_barrier
	s_setprio 0
	s_add_i32 s67, s67, 2
	s_add_u32 s80, s80, 0x100
	s_addc_u32 s81, s81, 0
	s_cmp_ge_u32 s67, s3
	s_cbranch_scc1 .LBB0_508

; #define PG8_SB(B) __builtin_amdgcn_rcpf(1.f + expneg(B))
; #define PG8_SB(B) __builtin_amdgcn_rcpf(1.f + expneg(B))
; #define PG8_STAGE(bufoff, gbase, voff) do { _Pragma("unroll") for (int _i = 0; _i < 2; ++_i) \
;         __builtin_amdgcn_global_load_lds((const unsigned*)((const char*)(gbase) + (size_t)_i * qstep + (voff)[0]), (PG8_LAS unsigned*)(lds + (bufoff) + ldsw + _i * 8192), 16, 0, 0); } while (0)
; #define PG8_LDA(dst, b, h) do { _Pragma("unroll") for (int m = 0; m < 4; ++m) _Pragma("unroll") for (int k = 0; k < 2; ++k) dst[m][k] = *(const PG8_LAS bf16x8*)(lds + PG8_SA(b, h) + aoff + m * 2048 + k * 1024); } while (0)
; #define PG8_LDB(dst, b, h) do { _Pragma("unroll") for (int n = 0; n < 2; ++n) _Pragma("unroll") for (int k = 0; k < 2; ++k) dst[n][k] = *(const PG8_LAS bf16x8*)(lds + PG8_SB(b, h) + boff + n * 2048 + k * 1024); } while (0)
; #define PG8_WAIT_V89() do { if constexpr (SLIVER) PG8_WAIT_V(9); else PG8_WAIT_V(8); } while (0)
; #define PG8_WAIT_L(n) asm volatile("s_waitcnt lgkmcnt(" #n ")" ::: "memory")
; #define PG8_BAR __builtin_amdgcn_s_barrier()
; #define PG8_SCHED __builtin_amdgcn_sched_barrier(0)
; template <class Epi, class Sched, bool ALIGN_EPI = false, bool SP2 = false, bool SLIVER = false>
; __device__ __forceinline__ void gemm_phase(PG8_LAS unsigned char* lds, const Gemm g, const Sched& S, const Epi& E) {
;     ...
;             const char* s1 = cS + (size_t)(t + 1) * kstep; const char* s2 = last ? nS : cS + (size_t)(t + 2) * kstep;
;             if (last && has_next) S.a_ready(nxt);
;             if constexpr (SP2) {
;             PG8_LDB(B0, 0, 0); PG8_LDB(B1, 0, 1); PG8_SCHED; PG8_LDA(At, 0, 0); PG8_STAGE(PG8_SA(1, 1), a1 + hstep, voffA); PG8_STAGE_S(1, s1);
;             PG8_WAIT_V89(); PG8_WAIT_L(0); PG8_BAR; PG8_MMA(0, 0, At, B0); PG8_MMA(0, 1, At, B1); PG8_BAR; PG8_SCHED;
;             PG8_LDA(At, 0, 1); PG8_LDS_S(0); PG8_STAGE(PG8_SB(0, 0), b2, voffB); PG8_STAGE(PG8_SB(0, 1), b2 + hstep, voffB); PG8_STAGE(PG8_SA(0, 0), a2, voffA);
;             PG8_WAIT_V89(); PG8_WAIT_L(0); PG8_BAR; PG8_MMA(1, 0, At, B0); PG8_MMA(1, 1, At, B1); PG8_MMA_S(); PG8_BAR; PG8_SCHED;
;             PG8_LDB(B0, 1, 0); PG8_LDB(B1, 1, 1); PG8_SCHED; PG8_LDA(At, 1, 0); PG8_STAGE(PG8_SA(0, 1), a2 + hstep, voffA); PG8_STAGE_S(0, s2);
;             PG8_WAIT_V89(); PG8_WAIT_L(0); PG8_BAR; PG8_MMA(0, 0, At, B0); PG8_MMA(0, 1, At, B1); PG8_BAR; PG8_SCHED;
.LBB0_502:
	s_barrier
	s_setprio 0
	s_add_u32 s68, s62, s80
	s_addc_u32 s69, s63, s81
	s_add_u32 s76, s68, 0x100
	s_addc_u32 s77, s69, 0
	s_and_b64 s[68:69], s[86:87], exec
	s_cselect_b32 s69, s85, s77
	s_cselect_b32 s68, s84, s76
	s_add_i32 s76, 0, 0x18000
	v_add_u32_e32 v82, s76, v239
	s_add_i32 s77, 0, 0x1c000
	ds_read_b128 v[146:149], v82
	ds_read_b128 v[150:153], v82 offset:1024
	ds_read_b128 v[154:157], v82 offset:2048
	ds_read_b128 v[158:161], v82 offset:3072
	v_add_u32_e32 v82, s77, v239
	ds_read_b128 v[166:169], v82
	ds_read_b128 v[170:173], v82 offset:1024
	ds_read_b128 v[174:177], v82 offset:2048
	ds_read_b128 v[162:165], v82 offset:3072
	s_mov_b32 m0, s91
	v_lshl_add_u64 v[208:209], v[194:195], 0, s[24:25]
	ds_read_b128 v[82:85], v242 offset:32768
	ds_read_b128 v[94:97], v242 offset:33792
	ds_read_b128 v[180:183], v242 offset:34816
	ds_read_b128 v[184:187], v242 offset:35840
	ds_read_b128 v[196:199], v242 offset:36864
	ds_read_b128 v[200:203], v242 offset:37888
	ds_read_b128 v[220:223], v242 offset:38912
	ds_read_b128 v[224:227], v242 offset:39936
	global_load_lds_dwordx4 v[208:209], off
	v_lshl_add_u64 v[208:209], v[194:195], 0, s[14:15]
	s_mov_b32 m0, s92
	s_nop 0
	global_load_lds_dwordx4 v[208:209], off
	v_lshl_add_u64 v[208:209], s[68:69], 0, v[214:215]
	s_mov_b32 m0, s93
	s_nop 0
	global_load_lds_dword v[208:209], off
	s_waitcnt vmcnt(9)
	s_waitcnt lgkmcnt(0)
	s_setprio 1
	s_barrier
	v_mfma_f32_16x16x32_bf16 v[134:137], v[146:149], v[82:85], v[134:137]
	v_mfma_f32_16x16x32_bf16 v[130:133], v[154:157], v[82:85], v[130:133]
	v_mfma_f32_16x16x32_bf16 v[126:129], v[146:149], v[180:183], v[126:129]
	v_mfma_f32_16x16x32_bf16 v[122:125], v[154:157], v[180:183], v[122:125]
	v_mfma_f32_16x16x32_bf16 v[118:121], v[146:149], v[196:199], v[118:121]
	v_mfma_f32_16x16x32_bf16 v[114:117], v[154:157], v[196:199], v[114:117]
	v_mfma_f32_16x16x32_bf16 v[110:113], v[146:149], v[220:223], v[110:113]
	v_mfma_f32_16x16x32_bf16 v[106:109], v[154:157], v[220:223], v[106:109]
	v_mfma_f32_16x16x32_bf16 v[134:137], v[150:153], v[94:97], v[134:137]
	v_mfma_f32_16x16x32_bf16 v[130:133], v[158:161], v[94:97], v[130:133]
	v_mfma_f32_16x16x32_bf16 v[126:129], v[150:153], v[184:187], v[126:129]
	v_mfma_f32_16x16x32_bf16 v[122:125], v[158:161], v[184:187], v[122:125]
	v_mfma_f32_16x16x32_bf16 v[118:121], v[150:153], v[200:203], v[118:121]
	v_mfma_f32_16x16x32_bf16 v[114:117], v[158:161], v[200:203], v[114:117]
	v_mfma_f32_16x16x32_bf16 v[110:113], v[150:153], v[224:227], v[110:113]
	v_mfma_f32_16x16x32_bf16 v[106:109], v[158:161], v[224:227], v[106:109]
	s_setprio 0
	s_setprio 1
	v_mfma_f32_16x16x32_bf16 v[102:105], v[166:169], v[82:85], v[102:105]
	v_mfma_f32_16x16x32_bf16 v[82:85], v[174:177], v[82:85], v[98:101]
	v_mfma_f32_16x16x32_bf16 v[98:101], v[162:165], v[94:97], v[82:85]
	v_mfma_f32_16x16x32_bf16 v[82:85], v[166:169], v[180:183], v[90:93]
	v_mfma_f32_16x16x32_bf16 v[90:93], v[170:173], v[184:187], v[82:85]
	v_mfma_f32_16x16x32_bf16 v[82:85], v[174:177], v[180:183], v[86:89]
	v_mfma_f32_16x16x32_bf16 v[78:81], v[166:169], v[196:199], v[78:81]
	v_mfma_f32_16x16x32_bf16 v[74:77], v[174:177], v[196:199], v[74:77]
	v_mfma_f32_16x16x32_bf16 v[70:73], v[166:169], v[220:223], v[70:73]
	v_mfma_f32_16x16x32_bf16 v[66:69], v[174:177], v[220:223], v[66:69]
	v_mfma_f32_16x16x32_bf16 v[102:105], v[170:173], v[94:97], v[102:105]
	v_mfma_f32_16x16x32_bf16 v[86:89], v[162:165], v[184:187], v[82:85]
	v_mfma_f32_16x16x32_bf16 v[78:81], v[170:173], v[200:203], v[78:81]
	v_mfma_f32_16x16x32_bf16 v[74:77], v[162:165], v[200:203], v[74:77]
	v_mfma_f32_16x16x32_bf16 v[70:73], v[170:173], v[224:227], v[70:73]
	v_mfma_f32_16x16x32_bf16 v[66:69], v[162:165], v[224:227], v[66:69]
	s_barrier
; #define PG8_SB(B) __builtin_amdgcn_rcpf(1.f + expneg(B))
; #define PG8_SB(B) __builtin_amdgcn_rcpf(1.f + expneg(B))
; #define PG8_STAGE(bufoff, gbase, voff) do { _Pragma("unroll") for (int _i = 0; _i < 2; ++_i) \
;         __builtin_amdgcn_global_load_lds((const unsigned*)((const char*)(gbase) + (size_t)_i * qstep + (voff)[0]), (PG8_LAS unsigned*)(lds + (bufoff) + ldsw + _i * 8192), 16, 0, 0); } while (0)
; #define PG8_LDA(dst, b, h) do { _Pragma("unroll") for (int m = 0; m < 4; ++m) _Pragma("unroll") for (int k = 0; k < 2; ++k) dst[m][k] = *(const PG8_LAS bf16x8*)(lds + PG8_SA(b, h) + aoff + m * 2048 + k * 1024); } while (0)
; #define PG8_MMA(ai, bj, At, Bt) do { __builtin_amdgcn_s_setprio(1); _Pragma("unroll") for (int m = 0; m < 4; ++m) _Pragma("unroll") for (int n = 0; n < 2; ++n) _Pragma("unroll") for (int k = 0; k < 2; ++k) \
;         acc[ai][bj][m][n] = __builtin_amdgcn_mfma_f32_16x16x32_bf16(Bt[n][k], At[m][k], acc[ai][bj][m][n], 0, 0, 0); __builtin_amdgcn_s_setprio(0); } while (0)
; #define PG8_WAIT_V89() do { if constexpr (SLIVER) PG8_WAIT_V(9); else PG8_WAIT_V(8); } while (0)
; #define PG8_LDS_S(b) do { if constexpr (SLIVER) { Sf[0] = *(const PG8_LAS bf16x8*)(lds + STAGE_BYTES + (b) * 2048 + soff0); Sf[1] = *(const PG8_LAS bf16x8*)(lds + STAGE_BYTES + (b) * 2048 + (soff0 ^ 64)); } } while (0)
; #define PG8_WAIT_L(n) asm volatile("s_waitcnt lgkmcnt(" #n ")" ::: "memory")
; #define PG8_BAR __builtin_amdgcn_s_barrier()
; #define PG8_SCHED __builtin_amdgcn_sched_barrier(0)
; template <class Epi, class Sched, bool ALIGN_EPI = false, bool SP2 = false, bool SLIVER = false>
; __device__ __forceinline__ void gemm_phase(PG8_LAS unsigned char* lds, const Gemm g, const Sched& S, const Epi& E) {
;     ...
;             PG8_LDA(At, 1, 1); PG8_LDS_S(1); PG8_STAGE(PG8_SB(1, 0), b3, voffB); PG8_STAGE(PG8_SB(1, 1), b3 + hstep, voffB); PG8_STAGE(PG8_SA(1, 0), a3, voffA);
;             PG8_WAIT_V89(); PG8_WAIT_L(0); PG8_BAR; PG8_MMA(1, 0, At, B0); PG8_MMA(1, 1, At, B1); PG8_MMA_S(); PG8_BAR; PG8_SCHED;
	s_setprio 0
	s_add_i32 s68, 0, 0x20800
	v_add_u32_e32 v178, s68, v240
	v_add_u32_e32 v184, s68, v241
	s_add_i32 s68, s76, s95
	v_lshl_add_u64 v[208:209], v[192:193], 0, s[26:27]
	s_mov_b32 m0, s68
	ds_read_b128 v[82:85], v242 offset:49152
	ds_read_b128 v[94:97], v242 offset:50176
	ds_read_b128 v[196:199], v242 offset:51200
	ds_read_b128 v[200:203], v242 offset:52224
	ds_read_b128 v[220:223], v242 offset:53248
	ds_read_b128 v[224:227], v242 offset:54272
	ds_read_b128 v[228:231], v242 offset:55296
	ds_read_b128 v[232:235], v242 offset:56320
	ds_read_b128 v[180:183], v178
	ds_read_b128 v[184:187], v184
	global_load_lds_dwordx4 v[208:209], off
	v_lshl_add_u64 v[208:209], v[192:193], 0, s[72:73]
	s_add_i32 m0, s68, 0x2000
	s_add_i32 s68, s77, s95
	global_load_lds_dwordx4 v[208:209], off
	v_lshl_add_u64 v[208:209], v[192:193], 0, s[34:35]
	s_mov_b32 m0, s68
	s_mov_b64 s[76:77], 0x120080
	global_load_lds_dwordx4 v[208:209], off
	v_lshl_add_u64 v[192:193], v[192:193], 0, s[76:77]
	s_add_i32 m0, s68, 0x2000
	s_nop 0
	global_load_lds_dwordx4 v[192:193], off
	v_lshl_add_u64 v[192:193], v[194:195], 0, s[26:27]
	s_mov_b32 m0, s97
	s_nop 0
	global_load_lds_dwordx4 v[192:193], off
	v_lshl_add_u64 v[192:193], v[194:195], 0, s[72:73]
	s_mov_b32 m0, s18
	s_nop 0
	global_load_lds_dwordx4 v[192:193], off
	s_waitcnt vmcnt(9)
	s_waitcnt lgkmcnt(0)
	s_setprio 1
	s_barrier
	v_mfma_f32_16x16x32_bf16 v[62:65], v[146:149], v[82:85], v[62:65]
	v_mfma_f32_16x16x32_bf16 v[58:61], v[154:157], v[82:85], v[58:61]
	v_mfma_f32_16x16x32_bf16 v[54:57], v[146:149], v[196:199], v[54:57]
	v_mfma_f32_16x16x32_bf16 v[50:53], v[154:157], v[196:199], v[50:53]
	v_mfma_f32_16x16x32_bf16 v[46:49], v[146:149], v[220:223], v[46:49]
	v_mfma_f32_16x16x32_bf16 v[42:45], v[154:157], v[220:223], v[42:45]
	v_mfma_f32_16x16x32_bf16 v[38:41], v[146:149], v[228:231], v[38:41]
	v_mfma_f32_16x16x32_bf16 v[34:37], v[154:157], v[228:231], v[34:37]
	v_mfma_f32_16x16x32_bf16 v[62:65], v[150:153], v[94:97], v[62:65]
	v_mfma_f32_16x16x32_bf16 v[58:61], v[158:161], v[94:97], v[58:61]
	v_mfma_f32_16x16x32_bf16 v[54:57], v[150:153], v[200:203], v[54:57]
	v_mfma_f32_16x16x32_bf16 v[50:53], v[158:161], v[200:203], v[50:53]
	v_mfma_f32_16x16x32_bf16 v[46:49], v[150:153], v[224:227], v[46:49]
	v_mfma_f32_16x16x32_bf16 v[42:45], v[158:161], v[224:227], v[42:45]
	v_mfma_f32_16x16x32_bf16 v[38:41], v[150:153], v[232:235], v[38:41]
	v_mfma_f32_16x16x32_bf16 v[34:37], v[158:161], v[232:235], v[34:37]
	s_setprio 0
	s_setprio 1
	v_mfma_f32_16x16x32_bf16 v[30:33], v[166:169], v[82:85], v[30:33]
	v_mfma_f32_16x16x32_bf16 v[26:29], v[174:177], v[82:85], v[26:29]
	v_mfma_f32_16x16x32_bf16 v[22:25], v[166:169], v[196:199], v[22:25]
	v_mfma_f32_16x16x32_bf16 v[18:21], v[174:177], v[196:199], v[18:21]
	v_mfma_f32_16x16x32_bf16 v[14:17], v[166:169], v[220:223], v[14:17]
	v_mfma_f32_16x16x32_bf16 v[10:13], v[174:177], v[220:223], v[10:13]
	v_mfma_f32_16x16x32_bf16 v[6:9], v[166:169], v[228:231], v[6:9]
	v_mfma_f32_16x16x32_bf16 v[2:5], v[174:177], v[228:231], v[2:5]
	v_mfma_f32_16x16x32_bf16 v[30:33], v[170:173], v[94:97], v[30:33]
	v_mfma_f32_16x16x32_bf16 v[26:29], v[162:165], v[94:97], v[26:29]
	v_mfma_f32_16x16x32_bf16 v[22:25], v[170:173], v[200:203], v[22:25]
	v_mfma_f32_16x16x32_bf16 v[18:21], v[162:165], v[200:203], v[18:21]
	v_mfma_f32_16x16x32_bf16 v[14:17], v[170:173], v[224:227], v[14:17]
	v_mfma_f32_16x16x32_bf16 v[10:13], v[162:165], v[224:227], v[10:13]
	v_mfma_f32_16x16x32_bf16 v[6:9], v[170:173], v[232:235], v[6:9]
	v_mfma_f32_16x16x32_bf16 v[2:5], v[162:165], v[232:235], v[2:5]
	s_setprio 0
	s_setprio 1
	s_and_b64 vcc, exec, s[40:41]
	s_mov_b64 s[40:41], -1
	s_mov_b64 s[86:87], 0x4000400
	s_mov_b64 s[88:89], 0x4000800
	s_cbranch_vccnz .LBB0_504
	v_mfma_f32_16x16x32_bf16 v[82:85], v[166:169], v[180:183], v[138:141]
	s_mov_b64 s[40:41], 0
	v_mfma_f32_16x16x32_bf16 v[94:97], v[174:177], v[180:183], v[142:145]
	v_mfma_f32_16x16x32_bf16 v[82:85], v[170:173], v[184:187], v[82:85]
	v_mfma_f32_16x16x32_bf16 v[94:97], v[162:165], v[184:187], v[94:97]

; #define PG8_SB(B) __builtin_amdgcn_rcpf(1.f + expneg(B))
; #define PG8_SB(B) __builtin_amdgcn_rcpf(1.f + expneg(B))
; #define PG8_STAGE(bufoff, gbase, voff) do { _Pragma("unroll") for (int _i = 0; _i < 2; ++_i) \
;         __builtin_amdgcn_global_load_lds((const unsigned*)((const char*)(gbase) + (size_t)_i * qstep + (voff)[0]), (PG8_LAS unsigned*)(lds + (bufoff) + ldsw + _i * 8192), 16, 0, 0); } while (0)
; #define PG8_LDA(dst, b, h) do { _Pragma("unroll") for (int m = 0; m < 4; ++m) _Pragma("unroll") for (int k = 0; k < 2; ++k) dst[m][k] = *(const PG8_LAS bf16x8*)(lds + PG8_SA(b, h) + aoff + m * 2048 + k * 1024); } while (0)
; #define PG8_LDB(dst, b, h) do { _Pragma("unroll") for (int n = 0; n < 2; ++n) _Pragma("unroll") for (int k = 0; k < 2; ++k) dst[n][k] = *(const PG8_LAS bf16x8*)(lds + PG8_SB(b, h) + boff + n * 2048 + k * 1024); } while (0)
; #define PG8_WAIT_V89() do { if constexpr (SLIVER) PG8_WAIT_V(9); else PG8_WAIT_V(8); } while (0)
; #define PG8_WAIT_L(n) asm volatile("s_waitcnt lgkmcnt(" #n ")" ::: "memory")
; #define PG8_BAR __builtin_amdgcn_s_barrier()
; #define PG8_SCHED __builtin_amdgcn_sched_barrier(0)
; template <class Epi, class Sched, bool ALIGN_EPI = false, bool SP2 = false, bool SLIVER = false>
; __device__ __forceinline__ void gemm_phase(PG8_LAS unsigned char* lds, const Gemm g, const Sched& S, const Epi& E) {
;     ...
;             const char* s1 = cS + (size_t)(t + 1) * kstep; const char* s2 = last ? nS : cS + (size_t)(t + 2) * kstep;
;             if (last && has_next) S.a_ready(nxt);
;             if constexpr (SP2) {
;             PG8_LDB(B0, 0, 0); PG8_LDB(B1, 0, 1); PG8_SCHED; PG8_LDA(At, 0, 0); PG8_STAGE(PG8_SA(1, 1), a1 + hstep, voffA); PG8_STAGE_S(1, s1);
;             PG8_WAIT_V89(); PG8_WAIT_L(0); PG8_BAR; PG8_MMA(0, 0, At, B0); PG8_MMA(0, 1, At, B1); PG8_BAR; PG8_SCHED;
;             PG8_LDA(At, 0, 1); PG8_LDS_S(0); PG8_STAGE(PG8_SB(0, 0), b2, voffB); PG8_STAGE(PG8_SB(0, 1), b2 + hstep, voffB); PG8_STAGE(PG8_SA(0, 0), a2, voffA);
;             PG8_WAIT_V89(); PG8_WAIT_L(0); PG8_BAR; PG8_MMA(1, 0, At, B0); PG8_MMA(1, 1, At, B1); PG8_MMA_S(); PG8_BAR; PG8_SCHED;
;             PG8_LDB(B0, 1, 0); PG8_LDB(B1, 1, 1); PG8_SCHED; PG8_LDA(At, 1, 0); PG8_STAGE(PG8_SA(0, 1), a2 + hstep, voffA); PG8_STAGE_S(0, s2);
;             PG8_WAIT_V89(); PG8_WAIT_L(0); PG8_BAR; PG8_MMA(0, 0, At, B0); PG8_MMA(0, 1, At, B1); PG8_BAR; PG8_SCHED;
.LBB0_602:
	s_barrier
	s_setprio 0
	s_add_u32 s77, s94, s62
	s_addc_u32 s78, s95, s63
	s_add_u32 s77, s77, 0x100
	s_addc_u32 s83, s78, 0
	s_and_b64 s[78:79], s[80:81], exec
	s_cselect_b32 s79, s66, s83
	s_cselect_b32 s78, s67, s77
	s_add_i32 s77, 0, 0x18000
	v_add_u32_e32 v2, s77, v212
	s_add_i32 s80, 0, 0x1c000
	ds_read_b128 v[146:149], v2
	ds_read_b128 v[150:153], v2 offset:1024
	ds_read_b128 v[154:157], v2 offset:2048
	ds_read_b128 v[158:161], v2 offset:3072
	v_add_u32_e32 v2, s80, v212
	ds_read_b128 v[166:169], v2
	ds_read_b128 v[170:173], v2 offset:1024
	ds_read_b128 v[174:177], v2 offset:2048
	ds_read_b128 v[162:165], v2 offset:3072
	s_mov_b32 m0, s49
	v_lshl_add_u64 v[208:209], v[210:211], 0, s[22:23]
	ds_read_b128 v[2:5], v215 offset:32768
	ds_read_b128 v[6:9], v215 offset:33792
	ds_read_b128 v[180:183], v215 offset:34816
	ds_read_b128 v[184:187], v215 offset:35840
	ds_read_b128 v[216:219], v215 offset:36864
	ds_read_b128 v[220:223], v215 offset:37888
	ds_read_b128 v[224:227], v215 offset:38912
	ds_read_b128 v[228:231], v215 offset:39936
	global_load_lds_dwordx4 v[208:209], off
	v_lshl_add_u64 v[208:209], v[210:211], 0, s[24:25]
	s_mov_b32 m0, s50
	s_nop 0
	global_load_lds_dwordx4 v[208:209], off
	v_lshl_add_u64 v[208:209], s[78:79], 0, v[192:193]
	s_mov_b32 m0, s51
	s_nop 0
	global_load_lds_dword v[208:209], off
	s_waitcnt vmcnt(9)
	s_waitcnt lgkmcnt(0)
	s_setprio 1
	s_barrier
	v_mfma_f32_16x16x32_bf16 v[134:137], v[146:149], v[2:5], v[134:137]
	v_mfma_f32_16x16x32_bf16 v[130:133], v[154:157], v[2:5], v[130:133]
	v_mfma_f32_16x16x32_bf16 v[118:121], v[146:149], v[180:183], v[118:121]
	v_mfma_f32_16x16x32_bf16 v[114:117], v[154:157], v[180:183], v[114:117]
	v_mfma_f32_16x16x32_bf16 v[102:105], v[146:149], v[216:219], v[102:105]
	v_mfma_f32_16x16x32_bf16 v[98:101], v[154:157], v[216:219], v[98:101]
	v_mfma_f32_16x16x32_bf16 v[86:89], v[146:149], v[224:227], v[86:89]
	v_mfma_f32_16x16x32_bf16 v[82:85], v[154:157], v[224:227], v[82:85]
	v_mfma_f32_16x16x32_bf16 v[134:137], v[150:153], v[6:9], v[134:137]
	v_mfma_f32_16x16x32_bf16 v[130:133], v[158:161], v[6:9], v[130:133]
	v_mfma_f32_16x16x32_bf16 v[118:121], v[150:153], v[184:187], v[118:121]
	v_mfma_f32_16x16x32_bf16 v[114:117], v[158:161], v[184:187], v[114:117]
	v_mfma_f32_16x16x32_bf16 v[102:105], v[150:153], v[220:223], v[102:105]
	v_mfma_f32_16x16x32_bf16 v[98:101], v[158:161], v[220:223], v[98:101]
	v_mfma_f32_16x16x32_bf16 v[86:89], v[150:153], v[228:231], v[86:89]
	v_mfma_f32_16x16x32_bf16 v[82:85], v[158:161], v[228:231], v[82:85]
	s_setprio 0
	s_setprio 1
	v_mfma_f32_16x16x32_bf16 v[126:129], v[166:169], v[2:5], v[126:129]
	v_mfma_f32_16x16x32_bf16 v[2:5], v[174:177], v[2:5], v[122:125]
	v_mfma_f32_16x16x32_bf16 v[122:125], v[162:165], v[6:9], v[2:5]
	v_mfma_f32_16x16x32_bf16 v[2:5], v[166:169], v[180:183], v[110:113]
	v_mfma_f32_16x16x32_bf16 v[110:113], v[170:173], v[184:187], v[2:5]
	v_mfma_f32_16x16x32_bf16 v[2:5], v[174:177], v[180:183], v[106:109]
	v_mfma_f32_16x16x32_bf16 v[106:109], v[162:165], v[184:187], v[2:5]
	v_mfma_f32_16x16x32_bf16 v[2:5], v[166:169], v[216:219], v[94:97]
	v_mfma_f32_16x16x32_bf16 v[94:97], v[170:173], v[220:223], v[2:5]
	v_mfma_f32_16x16x32_bf16 v[2:5], v[174:177], v[216:219], v[90:93]
	v_mfma_f32_16x16x32_bf16 v[90:93], v[162:165], v[220:223], v[2:5]
	v_mfma_f32_16x16x32_bf16 v[2:5], v[166:169], v[224:227], v[78:81]
	v_mfma_f32_16x16x32_bf16 v[78:81], v[170:173], v[228:231], v[2:5]
	v_mfma_f32_16x16x32_bf16 v[2:5], v[174:177], v[224:227], v[74:77]
	v_mfma_f32_16x16x32_bf16 v[126:129], v[170:173], v[6:9], v[126:129]
	v_mfma_f32_16x16x32_bf16 v[74:77], v[162:165], v[228:231], v[2:5]
	s_barrier
; #define PG8_SB(B) __builtin_amdgcn_rcpf(1.f + expneg(B))
; #define PG8_SB(B) __builtin_amdgcn_rcpf(1.f + expneg(B))
; #define PG8_STAGE(bufoff, gbase, voff) do { _Pragma("unroll") for (int _i = 0; _i < 2; ++_i) \
;         __builtin_amdgcn_global_load_lds((const unsigned*)((const char*)(gbase) + (size_t)_i * qstep + (voff)[0]), (PG8_LAS unsigned*)(lds + (bufoff) + ldsw + _i * 8192), 16, 0, 0); } while (0)
; #define PG8_LDA(dst, b, h) do { _Pragma("unroll") for (int m = 0; m < 4; ++m) _Pragma("unroll") for (int k = 0; k < 2; ++k) dst[m][k] = *(const PG8_LAS bf16x8*)(lds + PG8_SA(b, h) + aoff + m * 2048 + k * 1024); } while (0)
; #define PG8_MMA(ai, bj, At, Bt) do { __builtin_amdgcn_s_setprio(1); _Pragma("unroll") for (int m = 0; m < 4; ++m) _Pragma("unroll") for (int n = 0; n < 2; ++n) _Pragma("unroll") for (int k = 0; k < 2; ++k) \
;         acc[ai][bj][m][n] = __builtin_amdgcn_mfma_f32_16x16x32_bf16(Bt[n][k], At[m][k], acc[ai][bj][m][n], 0, 0, 0); __builtin_amdgcn_s_setprio(0); } while (0)
; #define PG8_WAIT_V89() do { if constexpr (SLIVER) PG8_WAIT_V(9); else PG8_WAIT_V(8); } while (0)
; #define PG8_LDS_S(b) do { if constexpr (SLIVER) { Sf[0] = *(const PG8_LAS bf16x8*)(lds + STAGE_BYTES + (b) * 2048 + soff0); Sf[1] = *(const PG8_LAS bf16x8*)(lds + STAGE_BYTES + (b) * 2048 + (soff0 ^ 64)); } } while (0)
; #define PG8_WAIT_L(n) asm volatile("s_waitcnt lgkmcnt(" #n ")" ::: "memory")
; #define PG8_BAR __builtin_amdgcn_s_barrier()
; #define PG8_SCHED __builtin_amdgcn_sched_barrier(0)
; template <class Epi, class Sched, bool ALIGN_EPI = false, bool SP2 = false, bool SLIVER = false>
; __device__ __forceinline__ void gemm_phase(PG8_LAS unsigned char* lds, const Gemm g, const Sched& S, const Epi& E) {
;     ...
;             PG8_LDA(At, 1, 1); PG8_LDS_S(1); PG8_STAGE(PG8_SB(1, 0), b3, voffB); PG8_STAGE(PG8_SB(1, 1), b3 + hstep, voffB); PG8_STAGE(PG8_SA(1, 0), a3, voffA);
;             PG8_WAIT_V89(); PG8_WAIT_L(0); PG8_BAR; PG8_MMA(1, 0, At, B0); PG8_MMA(1, 1, At, B1); PG8_MMA_S(); PG8_BAR; PG8_SCHED;
	s_setprio 0
	s_add_i32 s78, 0, 0x20800
	s_add_i32 s77, s77, s18
	v_add_u32_e32 v178, s78, v213
	v_add_u32_e32 v184, s78, v214
	v_lshl_add_u64 v[208:209], v[202:203], 0, s[26:27]
	s_mov_b32 m0, s77
	ds_read_b128 v[2:5], v215 offset:49152
	ds_read_b128 v[6:9], v215 offset:50176
	ds_read_b128 v[216:219], v215 offset:51200
	ds_read_b128 v[220:223], v215 offset:52224
	ds_read_b128 v[224:227], v215 offset:53248
	ds_read_b128 v[228:231], v215 offset:54272
	ds_read_b128 v[232:235], v215 offset:55296
	ds_read_b128 v[240:243], v215 offset:56320
	ds_read_b128 v[180:183], v178
	ds_read_b128 v[184:187], v184
	global_load_lds_dwordx4 v[208:209], off
	v_lshl_add_u64 v[208:209], v[202:203], 0, s[28:29]
	s_add_i32 m0, s77, 0x2000
	s_add_i32 s77, s80, s18
	global_load_lds_dwordx4 v[208:209], off
	v_lshl_add_u64 v[208:209], v[202:203], 0, s[30:31]
	s_mov_b32 m0, s77
	v_lshl_add_u64 v[202:203], v[202:203], 0, s[34:35]
	global_load_lds_dwordx4 v[208:209], off
	s_add_i32 m0, s77, 0x2000
	s_nop 0
	global_load_lds_dwordx4 v[202:203], off
	v_lshl_add_u64 v[202:203], v[210:211], 0, s[26:27]
	s_mov_b32 m0, s10
	s_nop 0
	global_load_lds_dwordx4 v[202:203], off
	v_lshl_add_u64 v[202:203], v[210:211], 0, s[28:29]
	s_mov_b32 m0, s2
	s_nop 0
	global_load_lds_dwordx4 v[202:203], off
	s_waitcnt vmcnt(9)
	s_waitcnt lgkmcnt(0)
	s_setprio 1
	s_barrier
	v_mfma_f32_16x16x32_bf16 v[70:73], v[146:149], v[2:5], v[70:73]
	v_mfma_f32_16x16x32_bf16 v[66:69], v[154:157], v[2:5], v[66:69]
	v_mfma_f32_16x16x32_bf16 v[54:57], v[146:149], v[216:219], v[54:57]
	v_mfma_f32_16x16x32_bf16 v[50:53], v[154:157], v[216:219], v[50:53]
	v_mfma_f32_16x16x32_bf16 v[38:41], v[146:149], v[224:227], v[38:41]
	v_mfma_f32_16x16x32_bf16 v[34:37], v[154:157], v[224:227], v[34:37]
	v_mfma_f32_16x16x32_bf16 v[22:25], v[146:149], v[232:235], v[22:25]
	v_mfma_f32_16x16x32_bf16 v[18:21], v[154:157], v[232:235], v[18:21]
	v_mfma_f32_16x16x32_bf16 v[70:73], v[150:153], v[6:9], v[70:73]
	v_mfma_f32_16x16x32_bf16 v[66:69], v[158:161], v[6:9], v[66:69]
	v_mfma_f32_16x16x32_bf16 v[54:57], v[150:153], v[220:223], v[54:57]
	v_mfma_f32_16x16x32_bf16 v[50:53], v[158:161], v[220:223], v[50:53]
	v_mfma_f32_16x16x32_bf16 v[38:41], v[150:153], v[228:231], v[38:41]
	v_mfma_f32_16x16x32_bf16 v[34:37], v[158:161], v[228:231], v[34:37]
	v_mfma_f32_16x16x32_bf16 v[22:25], v[150:153], v[240:243], v[22:25]
	v_mfma_f32_16x16x32_bf16 v[18:21], v[158:161], v[240:243], v[18:21]
	s_setprio 0
	s_setprio 1
	v_mfma_f32_16x16x32_bf16 v[62:65], v[166:169], v[2:5], v[62:65]
	v_mfma_f32_16x16x32_bf16 v[2:5], v[174:177], v[2:5], v[58:61]
	v_mfma_f32_16x16x32_bf16 v[58:61], v[162:165], v[6:9], v[2:5]
	v_mfma_f32_16x16x32_bf16 v[2:5], v[166:169], v[216:219], v[46:49]
	v_mfma_f32_16x16x32_bf16 v[46:49], v[170:173], v[220:223], v[2:5]
	v_mfma_f32_16x16x32_bf16 v[2:5], v[174:177], v[216:219], v[42:45]
	v_mfma_f32_16x16x32_bf16 v[42:45], v[162:165], v[220:223], v[2:5]
	v_mfma_f32_16x16x32_bf16 v[2:5], v[166:169], v[224:227], v[30:33]
	v_mfma_f32_16x16x32_bf16 v[30:33], v[170:173], v[228:231], v[2:5]
	v_mfma_f32_16x16x32_bf16 v[2:5], v[174:177], v[224:227], v[26:29]
	v_mfma_f32_16x16x32_bf16 v[26:29], v[162:165], v[228:231], v[2:5]
	v_mfma_f32_16x16x32_bf16 v[2:5], v[166:169], v[232:235], v[14:17]
	v_mfma_f32_16x16x32_bf16 v[14:17], v[170:173], v[240:243], v[2:5]
	v_mfma_f32_16x16x32_bf16 v[2:5], v[174:177], v[232:235], v[10:13]
	v_mfma_f32_16x16x32_bf16 v[62:65], v[170:173], v[6:9], v[62:65]
	v_mfma_f32_16x16x32_bf16 v[10:13], v[162:165], v[240:243], v[2:5]
	s_setprio 0
	s_setprio 1
	s_and_b64 vcc, exec, s[40:41]
	s_mov_b64 s[40:41], -1
	s_cbranch_vccnz .LBB0_604
	v_mfma_f32_16x16x32_bf16 v[2:5], v[166:169], v[180:183], v[138:141]
	s_mov_b64 s[40:41], 0
	v_mfma_f32_16x16x32_bf16 v[6:9], v[170:173], v[184:187], v[2:5]
	v_mfma_f32_16x16x32_bf16 v[2:5], v[174:177], v[180:183], v[142:145]
	v_mfma_f32_16x16x32_bf16 v[2:5], v[162:165], v[184:187], v[2:5]

; #define PG8_SB(B) __builtin_amdgcn_rcpf(1.f + expneg(B))
; #define PG8_SB(B) __builtin_amdgcn_rcpf(1.f + expneg(B))
; #define PG8_STAGE(bufoff, gbase, voff) do { _Pragma("unroll") for (int _i = 0; _i < 2; ++_i) \
;         __builtin_amdgcn_global_load_lds((const unsigned*)((const char*)(gbase) + (size_t)_i * qstep + (voff)[0]), (PG8_LAS unsigned*)(lds + (bufoff) + ldsw + _i * 8192), 16, 0, 0); } while (0)
; #define PG8_LDA(dst, b, h) do { _Pragma("unroll") for (int m = 0; m < 4; ++m) _Pragma("unroll") for (int k = 0; k < 2; ++k) dst[m][k] = *(const PG8_LAS bf16x8*)(lds + PG8_SA(b, h) + aoff + m * 2048 + k * 1024); } while (0)
; #define PG8_LDB(dst, b, h) do { _Pragma("unroll") for (int n = 0; n < 2; ++n) _Pragma("unroll") for (int k = 0; k < 2; ++k) dst[n][k] = *(const PG8_LAS bf16x8*)(lds + PG8_SB(b, h) + boff + n * 2048 + k * 1024); } while (0)
; #define PG8_WAIT_V89() do { if constexpr (SLIVER) PG8_WAIT_V(9); else PG8_WAIT_V(8); } while (0)
; #define PG8_WAIT_L(n) asm volatile("s_waitcnt lgkmcnt(" #n ")" ::: "memory")
; #define PG8_BAR __builtin_amdgcn_s_barrier()
; #define PG8_SCHED __builtin_amdgcn_sched_barrier(0)
; template <class Epi, class Sched, bool ALIGN_EPI = false, bool SP2 = false, bool SLIVER = false>
; __device__ __forceinline__ void gemm_phase(PG8_LAS unsigned char* lds, const Gemm g, const Sched& S, const Epi& E) {
;     ...
;             const char* s1 = cS + (size_t)(t + 1) * kstep; const char* s2 = last ? nS : cS + (size_t)(t + 2) * kstep;
;             if (last && has_next) S.a_ready(nxt);
;             if constexpr (SP2) {
;             PG8_LDB(B0, 0, 0); PG8_LDB(B1, 0, 1); PG8_SCHED; PG8_LDA(At, 0, 0); PG8_STAGE(PG8_SA(1, 1), a1 + hstep, voffA); PG8_STAGE_S(1, s1);
;             PG8_WAIT_V89(); PG8_WAIT_L(0); PG8_BAR; PG8_MMA(0, 0, At, B0); PG8_MMA(0, 1, At, B1); PG8_BAR; PG8_SCHED;
;             PG8_LDA(At, 0, 1); PG8_LDS_S(0); PG8_STAGE(PG8_SB(0, 0), b2, voffB); PG8_STAGE(PG8_SB(0, 1), b2 + hstep, voffB); PG8_STAGE(PG8_SA(0, 0), a2, voffA);
;             PG8_WAIT_V89(); PG8_WAIT_L(0); PG8_BAR; PG8_MMA(1, 0, At, B0); PG8_MMA(1, 1, At, B1); PG8_MMA_S(); PG8_BAR; PG8_SCHED;
;             PG8_LDB(B0, 1, 0); PG8_LDB(B1, 1, 1); PG8_SCHED; PG8_LDA(At, 1, 0); PG8_STAGE(PG8_SA(0, 1), a2 + hstep, voffA); PG8_STAGE_S(0, s2);
;             PG8_WAIT_V89(); PG8_WAIT_L(0); PG8_BAR; PG8_MMA(0, 0, At, B0); PG8_MMA(0, 1, At, B1); PG8_BAR; PG8_SCHED;
.LBB0_815:
	s_barrier
	s_setprio 0
	s_add_u32 s13, s92, s62
	s_addc_u32 s66, s93, s63
	s_add_u32 s13, s13, 0x100
	s_addc_u32 s68, s66, 0
	s_and_b64 s[66:67], s[80:81], exec
	s_cselect_b32 s67, s89, s68
	s_cselect_b32 s66, s88, s13
	s_add_i32 s13, 0, 0x18000
	v_add_u32_e32 v2, s13, v220
	s_add_i32 s68, 0, 0x1c000
	ds_read_b128 v[154:157], v2
	ds_read_b128 v[158:161], v2 offset:1024
	ds_read_b128 v[162:165], v2 offset:2048
	ds_read_b128 v[174:177], v2 offset:3072
	v_add_u32_e32 v2, s68, v220
	ds_read_b128 v[184:187], v2
	ds_read_b128 v[188:191], v2 offset:1024
	ds_read_b128 v[192:195], v2 offset:2048
	ds_read_b128 v[180:183], v2 offset:3072
	s_mov_b32 m0, s53
	v_lshl_add_u64 v[166:167], v[218:219], 0, s[0:1]
	ds_read_b128 v[2:5], v223 offset:32768
	ds_read_b128 v[6:9], v223 offset:33792
	ds_read_b128 v[82:85], v223 offset:34816
	ds_read_b128 v[86:89], v223 offset:35840
	ds_read_b128 v[224:227], v223 offset:36864
	ds_read_b128 v[228:231], v223 offset:37888
	ds_read_b128 v[232:235], v223 offset:38912
	ds_read_b128 v[240:243], v223 offset:39936
	global_load_lds_dwordx4 v[166:167], off
	v_lshl_add_u64 v[166:167], v[218:219], 0, s[74:75]
	s_mov_b32 m0, s54
	s_nop 0
	global_load_lds_dwordx4 v[166:167], off
	v_lshl_add_u64 v[166:167], s[66:67], 0, v[200:201]
	s_mov_b32 m0, s55
	s_nop 0
	global_load_lds_dword v[166:167], off
	s_waitcnt vmcnt(9)
	s_waitcnt lgkmcnt(0)
	s_setprio 1
	s_barrier
	v_mfma_f32_16x16x32_bf16 v[146:149], v[154:157], v[2:5], v[146:149]
	v_mfma_f32_16x16x32_bf16 v[170:173], v[158:161], v[6:9], v[146:149]
	v_mfma_f32_16x16x32_bf16 v[146:149], v[162:165], v[2:5], v[150:153]
	v_mfma_f32_16x16x32_bf16 v[134:137], v[154:157], v[82:85], v[134:137]
	v_mfma_f32_16x16x32_bf16 v[130:133], v[162:165], v[82:85], v[130:133]
	v_mfma_f32_16x16x32_bf16 v[118:121], v[154:157], v[224:227], v[118:121]
	v_mfma_f32_16x16x32_bf16 v[114:117], v[162:165], v[224:227], v[114:117]
	v_mfma_f32_16x16x32_bf16 v[102:105], v[154:157], v[232:235], v[102:105]
	v_mfma_f32_16x16x32_bf16 v[98:101], v[162:165], v[232:235], v[98:101]
	v_mfma_f32_16x16x32_bf16 v[166:169], v[174:177], v[6:9], v[146:149]
	v_mfma_f32_16x16x32_bf16 v[134:137], v[158:161], v[86:89], v[134:137]
	v_mfma_f32_16x16x32_bf16 v[130:133], v[174:177], v[86:89], v[130:133]
	v_mfma_f32_16x16x32_bf16 v[118:121], v[158:161], v[228:231], v[118:121]
	v_mfma_f32_16x16x32_bf16 v[114:117], v[174:177], v[228:231], v[114:117]
	v_mfma_f32_16x16x32_bf16 v[102:105], v[158:161], v[240:243], v[102:105]
	v_mfma_f32_16x16x32_bf16 v[98:101], v[174:177], v[240:243], v[98:101]
	s_setprio 0
	s_setprio 1
	v_mfma_f32_16x16x32_bf16 v[142:145], v[184:187], v[2:5], v[142:145]
	v_mfma_f32_16x16x32_bf16 v[2:5], v[192:195], v[2:5], v[138:141]
	v_mfma_f32_16x16x32_bf16 v[138:141], v[180:183], v[6:9], v[2:5]
	v_mfma_f32_16x16x32_bf16 v[2:5], v[184:187], v[82:85], v[126:129]
	v_mfma_f32_16x16x32_bf16 v[126:129], v[188:191], v[86:89], v[2:5]
	v_mfma_f32_16x16x32_bf16 v[2:5], v[192:195], v[82:85], v[122:125]
	v_mfma_f32_16x16x32_bf16 v[122:125], v[180:183], v[86:89], v[2:5]
	v_mfma_f32_16x16x32_bf16 v[2:5], v[184:187], v[224:227], v[110:113]
	v_mfma_f32_16x16x32_bf16 v[110:113], v[188:191], v[228:231], v[2:5]
	v_mfma_f32_16x16x32_bf16 v[2:5], v[192:195], v[224:227], v[106:109]
	v_mfma_f32_16x16x32_bf16 v[106:109], v[180:183], v[228:231], v[2:5]
	v_mfma_f32_16x16x32_bf16 v[2:5], v[184:187], v[232:235], v[94:97]
	v_mfma_f32_16x16x32_bf16 v[94:97], v[188:191], v[240:243], v[2:5]
	v_mfma_f32_16x16x32_bf16 v[2:5], v[192:195], v[232:235], v[90:93]
	v_mfma_f32_16x16x32_bf16 v[142:145], v[188:191], v[6:9], v[142:145]
	v_mfma_f32_16x16x32_bf16 v[90:93], v[180:183], v[240:243], v[2:5]
	s_barrier
; #define PG8_SB(B) __builtin_amdgcn_rcpf(1.f + expneg(B))
; #define PG8_SB(B) __builtin_amdgcn_rcpf(1.f + expneg(B))
; #define PG8_STAGE(bufoff, gbase, voff) do { _Pragma("unroll") for (int _i = 0; _i < 2; ++_i) \
;         __builtin_amdgcn_global_load_lds((const unsigned*)((const char*)(gbase) + (size_t)_i * qstep + (voff)[0]), (PG8_LAS unsigned*)(lds + (bufoff) + ldsw + _i * 8192), 16, 0, 0); } while (0)
; #define PG8_LDA(dst, b, h) do { _Pragma("unroll") for (int m = 0; m < 4; ++m) _Pragma("unroll") for (int k = 0; k < 2; ++k) dst[m][k] = *(const PG8_LAS bf16x8*)(lds + PG8_SA(b, h) + aoff + m * 2048 + k * 1024); } while (0)
; #define PG8_MMA(ai, bj, At, Bt) do { __builtin_amdgcn_s_setprio(1); _Pragma("unroll") for (int m = 0; m < 4; ++m) _Pragma("unroll") for (int n = 0; n < 2; ++n) _Pragma("unroll") for (int k = 0; k < 2; ++k) \
;         acc[ai][bj][m][n] = __builtin_amdgcn_mfma_f32_16x16x32_bf16(Bt[n][k], At[m][k], acc[ai][bj][m][n], 0, 0, 0); __builtin_amdgcn_s_setprio(0); } while (0)
; #define PG8_WAIT_V89() do { if constexpr (SLIVER) PG8_WAIT_V(9); else PG8_WAIT_V(8); } while (0)
; #define PG8_LDS_S(b) do { if constexpr (SLIVER) { Sf[0] = *(const PG8_LAS bf16x8*)(lds + STAGE_BYTES + (b) * 2048 + soff0); Sf[1] = *(const PG8_LAS bf16x8*)(lds + STAGE_BYTES + (b) * 2048 + (soff0 ^ 64)); } } while (0)
; #define PG8_WAIT_L(n) asm volatile("s_waitcnt lgkmcnt(" #n ")" ::: "memory")
; #define PG8_BAR __builtin_amdgcn_s_barrier()
; #define PG8_SCHED __builtin_amdgcn_sched_barrier(0)
; template <class Epi, class Sched, bool ALIGN_EPI = false, bool SP2 = false, bool SLIVER = false>
; __device__ __forceinline__ void gemm_phase(PG8_LAS unsigned char* lds, const Gemm g, const Sched& S, const Epi& E) {
;     ...
;             PG8_LDA(At, 1, 1); PG8_LDS_S(1); PG8_STAGE(PG8_SB(1, 0), b3, voffB); PG8_STAGE(PG8_SB(1, 1), b3 + hstep, voffB); PG8_STAGE(PG8_SA(1, 0), a3, voffA);
;             PG8_WAIT_V89(); PG8_WAIT_L(0); PG8_BAR; PG8_MMA(1, 0, At, B0); PG8_MMA(1, 1, At, B1); PG8_MMA_S(); PG8_BAR; PG8_SCHED;
	s_setprio 0
	s_add_i32 s66, 0, 0x20800
	v_add_u32_e32 v82, s66, v221
	v_add_u32_e32 v83, s66, v222
	s_add_i32 s13, s13, s18
	ds_read_b128 v[2:5], v223 offset:49152
	ds_read_b128 v[6:9], v223 offset:50176
	ds_read_b128 v[224:227], v223 offset:51200
	ds_read_b128 v[228:231], v223 offset:52224
	ds_read_b128 v[232:235], v223 offset:53248
	ds_read_b128 v[240:243], v223 offset:54272
	ds_read_b128 v[244:247], v223 offset:55296
	ds_read_b128 v[248:251], v223 offset:56320
	ds_read_b128 v[146:149], v82
	ds_read_b128 v[150:153], v83
	v_lshl_add_u64 v[82:83], v[216:217], 0, s[26:27]
	s_mov_b32 m0, s13
	s_mov_b64 s[66:67], 0x210080
	global_load_lds_dwordx4 v[82:83], off
	v_lshl_add_u64 v[82:83], v[216:217], 0, s[60:61]
	s_add_i32 m0, s13, 0x2000
	s_add_i32 s13, s68, s18
	global_load_lds_dwordx4 v[82:83], off
	v_lshl_add_u64 v[82:83], v[216:217], 0, s[8:9]
	s_mov_b32 m0, s13
	s_nop 0
	global_load_lds_dwordx4 v[82:83], off
	v_lshl_add_u64 v[82:83], v[216:217], 0, s[66:67]
	s_add_i32 m0, s13, 0x2000
	s_nop 0
	global_load_lds_dwordx4 v[82:83], off
	v_lshl_add_u64 v[82:83], v[218:219], 0, s[26:27]
	s_mov_b32 m0, s10
	s_nop 0
	global_load_lds_dwordx4 v[82:83], off
	v_lshl_add_u64 v[82:83], v[218:219], 0, s[60:61]
	s_mov_b32 m0, s48
	s_nop 0
	global_load_lds_dwordx4 v[82:83], off
	s_waitcnt vmcnt(9)
	s_waitcnt lgkmcnt(0)
	s_setprio 1
	s_barrier
	v_mfma_f32_16x16x32_bf16 v[74:77], v[154:157], v[2:5], v[74:77]
	v_mfma_f32_16x16x32_bf16 v[86:89], v[158:161], v[6:9], v[74:77]
	v_mfma_f32_16x16x32_bf16 v[74:77], v[162:165], v[2:5], v[78:81]
	v_mfma_f32_16x16x32_bf16 v[54:57], v[154:157], v[224:227], v[54:57]
	v_mfma_f32_16x16x32_bf16 v[50:53], v[162:165], v[224:227], v[50:53]
	v_mfma_f32_16x16x32_bf16 v[38:41], v[154:157], v[232:235], v[38:41]
	v_mfma_f32_16x16x32_bf16 v[34:37], v[162:165], v[232:235], v[34:37]
	v_mfma_f32_16x16x32_bf16 v[22:25], v[154:157], v[244:247], v[22:25]
	v_mfma_f32_16x16x32_bf16 v[18:21], v[162:165], v[244:247], v[18:21]
	v_mfma_f32_16x16x32_bf16 v[82:85], v[174:177], v[6:9], v[74:77]
	v_mfma_f32_16x16x32_bf16 v[54:57], v[158:161], v[228:231], v[54:57]
	v_mfma_f32_16x16x32_bf16 v[50:53], v[174:177], v[228:231], v[50:53]
	v_mfma_f32_16x16x32_bf16 v[38:41], v[158:161], v[240:243], v[38:41]
	v_mfma_f32_16x16x32_bf16 v[34:37], v[174:177], v[240:243], v[34:37]
	v_mfma_f32_16x16x32_bf16 v[22:25], v[158:161], v[248:251], v[22:25]
	v_mfma_f32_16x16x32_bf16 v[18:21], v[174:177], v[248:251], v[18:21]
	s_setprio 0
	s_setprio 1
	v_mfma_f32_16x16x32_bf16 v[62:65], v[184:187], v[2:5], v[62:65]
	v_mfma_f32_16x16x32_bf16 v[2:5], v[192:195], v[2:5], v[58:61]
	v_mfma_f32_16x16x32_bf16 v[58:61], v[180:183], v[6:9], v[2:5]
	v_mfma_f32_16x16x32_bf16 v[2:5], v[184:187], v[224:227], v[46:49]
	v_mfma_f32_16x16x32_bf16 v[46:49], v[188:191], v[228:231], v[2:5]
	v_mfma_f32_16x16x32_bf16 v[2:5], v[192:195], v[224:227], v[42:45]
	v_mfma_f32_16x16x32_bf16 v[42:45], v[180:183], v[228:231], v[2:5]
	v_mfma_f32_16x16x32_bf16 v[2:5], v[184:187], v[232:235], v[30:33]
	v_mfma_f32_16x16x32_bf16 v[30:33], v[188:191], v[240:243], v[2:5]
	v_mfma_f32_16x16x32_bf16 v[2:5], v[192:195], v[232:235], v[26:29]
	v_mfma_f32_16x16x32_bf16 v[26:29], v[180:183], v[240:243], v[2:5]
	v_mfma_f32_16x16x32_bf16 v[2:5], v[184:187], v[244:247], v[14:17]
	v_mfma_f32_16x16x32_bf16 v[14:17], v[188:191], v[248:251], v[2:5]
	v_mfma_f32_16x16x32_bf16 v[2:5], v[192:195], v[244:247], v[10:13]
	v_mfma_f32_16x16x32_bf16 v[62:65], v[188:191], v[6:9], v[62:65]
	v_mfma_f32_16x16x32_bf16 v[10:13], v[180:183], v[248:251], v[2:5]
	s_setprio 0
	s_setprio 1
	s_and_b64 vcc, exec, s[40:41]
	s_mov_b64 s[40:41], -1
	s_cbranch_vccnz .LBB0_817
	v_mfma_f32_16x16x32_bf16 v[2:5], v[184:187], v[146:149], v[66:69]
	s_mov_b64 s[40:41], 0
	v_mfma_f32_16x16x32_bf16 v[6:9], v[188:191], v[150:153], v[2:5]
	v_mfma_f32_16x16x32_bf16 v[2:5], v[192:195], v[146:149], v[70:73]
	v_mfma_f32_16x16x32_bf16 v[2:5], v[180:183], v[150:153], v[2:5]

; #define PG8_MMA(ai, bj, At, Bt) do { __builtin_amdgcn_s_setprio(1); _Pragma("unroll") for (int m = 0; m < 4; ++m) _Pragma("unroll") for (int n = 0; n < 2; ++n) _Pragma("unroll") for (int k = 0; k < 2; ++k) \
;         acc[ai][bj][m][n] = __builtin_amdgcn_mfma_f32_16x16x32_bf16(Bt[n][k], At[m][k], acc[ai][bj][m][n], 0, 0, 0); __builtin_amdgcn_s_setprio(0); } while (0)
; #define PG8_WAIT_V89() do { if constexpr (SLIVER) PG8_WAIT_V(9); else PG8_WAIT_V(8); } while (0)
; #define PG8_WAIT_L(n) asm volatile("s_waitcnt lgkmcnt(" #n ")" ::: "memory")
; #define PG8_BAR __builtin_amdgcn_s_barrier()
; #define PG8_SCHED __builtin_amdgcn_sched_barrier(0)
; template <class Epi, class Sched, bool ALIGN_EPI = false, bool SP2 = false, bool SLIVER = false>
; __device__ __forceinline__ void gemm_phase(PG8_LAS unsigned char* lds, const Gemm g, const Sched& S, const Epi& E) {
;     ...
;         for (int t = 0; t < nt; t += 2) {
;             const bool last = (t == nt - 2);
;             const char* a1 = cA + (size_t)(t + 1) * kstep;
;             const char* a2 = last ? nA : cA + (size_t)(t + 2) * kstep; const char* b2 = last ? nB : cB + (size_t)(t + 2) * kstep;
;     ...
;             PG8_WAIT_V89(); PG8_WAIT_L(0); PG8_BAR; PG8_MMA(1, 0, At, B0); PG8_MMA(1, 1, At, B1); PG8_MMA_S(); PG8_BAR; PG8_SCHED;
.LBB0_933:
	s_barrier
	s_setprio 0
	s_add_i32 s67, s67, 2
	s_add_u32 s62, s62, 0x100
	s_addc_u32 s63, s63, 0
	s_cmp_ge_u32 s67, s2
	s_cbranch_scc1 .LBB0_944

; #define PG8_SB(B) __builtin_amdgcn_rcpf(1.f + expneg(B))
; #define PG8_SB(B) __builtin_amdgcn_rcpf(1.f + expneg(B))
; #define PG8_STAGE(bufoff, gbase, voff) do { _Pragma("unroll") for (int _i = 0; _i < 2; ++_i) \
;         __builtin_amdgcn_global_load_lds((const unsigned*)((const char*)(gbase) + (size_t)_i * qstep + (voff)[0]), (PG8_LAS unsigned*)(lds + (bufoff) + ldsw + _i * 8192), 16, 0, 0); } while (0)
; #define PG8_LDA(dst, b, h) do { _Pragma("unroll") for (int m = 0; m < 4; ++m) _Pragma("unroll") for (int k = 0; k < 2; ++k) dst[m][k] = *(const PG8_LAS bf16x8*)(lds + PG8_SA(b, h) + aoff + m * 2048 + k * 1024); } while (0)
; #define PG8_LDB(dst, b, h) do { _Pragma("unroll") for (int n = 0; n < 2; ++n) _Pragma("unroll") for (int k = 0; k < 2; ++k) dst[n][k] = *(const PG8_LAS bf16x8*)(lds + PG8_SB(b, h) + boff + n * 2048 + k * 1024); } while (0)
; #define PG8_WAIT_V89() do { if constexpr (SLIVER) PG8_WAIT_V(9); else PG8_WAIT_V(8); } while (0)
; #define PG8_WAIT_L(n) asm volatile("s_waitcnt lgkmcnt(" #n ")" ::: "memory")
; #define PG8_BAR __builtin_amdgcn_s_barrier()
; #define PG8_SCHED __builtin_amdgcn_sched_barrier(0)
; template <class Epi, class Sched, bool ALIGN_EPI = false, bool SP2 = false, bool SLIVER = false>
; __device__ __forceinline__ void gemm_phase(PG8_LAS unsigned char* lds, const Gemm g, const Sched& S, const Epi& E) {
;     ...
;             const char* s1 = cS + (size_t)(t + 1) * kstep; const char* s2 = last ? nS : cS + (size_t)(t + 2) * kstep;
;             if (last && has_next) S.a_ready(nxt);
;             if constexpr (SP2) {
;             PG8_LDB(B0, 0, 0); PG8_LDB(B1, 0, 1); PG8_SCHED; PG8_LDA(At, 0, 0); PG8_STAGE(PG8_SA(1, 1), a1 + hstep, voffA); PG8_STAGE_S(1, s1);
;             PG8_WAIT_V89(); PG8_WAIT_L(0); PG8_BAR; PG8_MMA(0, 0, At, B0); PG8_MMA(0, 1, At, B1); PG8_BAR; PG8_SCHED;
;             PG8_LDA(At, 0, 1); PG8_LDS_S(0); PG8_STAGE(PG8_SB(0, 0), b2, voffB); PG8_STAGE(PG8_SB(0, 1), b2 + hstep, voffB); PG8_STAGE(PG8_SA(0, 0), a2, voffA);
;             PG8_WAIT_V89(); PG8_WAIT_L(0); PG8_BAR; PG8_MMA(1, 0, At, B0); PG8_MMA(1, 1, At, B1); PG8_MMA_S(); PG8_BAR; PG8_SCHED;
;             PG8_LDB(B0, 1, 0); PG8_LDB(B1, 1, 1); PG8_SCHED; PG8_LDA(At, 1, 0); PG8_STAGE(PG8_SA(0, 1), a2 + hstep, voffA); PG8_STAGE_S(0, s2);
;             PG8_WAIT_V89(); PG8_WAIT_L(0); PG8_BAR; PG8_MMA(0, 0, At, B0); PG8_MMA(0, 1, At, B1); PG8_BAR; PG8_SCHED;
.LBB0_938:
	s_barrier
	s_setprio 0
	s_add_u32 s12, s54, s62
	s_addc_u32 s13, s55, s63
	s_add_u32 s68, s12, 0x100
	s_addc_u32 s69, s13, 0
	s_and_b64 s[12:13], s[80:81], exec
	s_cselect_b32 s13, s19, s69
	s_cselect_b32 s12, s18, s68
	s_add_i32 s68, 0, 0x18000
	v_add_u32_e32 v2, s68, v212
	s_add_i32 s69, 0, 0x1c000
	ds_read_b128 v[146:149], v2
	ds_read_b128 v[150:153], v2 offset:1024
	ds_read_b128 v[154:157], v2 offset:2048
	ds_read_b128 v[158:161], v2 offset:3072
	v_add_u32_e32 v2, s69, v212
	ds_read_b128 v[166:169], v2
	ds_read_b128 v[170:173], v2 offset:1024
	ds_read_b128 v[174:177], v2 offset:2048
	ds_read_b128 v[162:165], v2 offset:3072
	s_mov_b32 m0, s49
	v_lshl_add_u64 v[208:209], v[210:211], 0, s[46:47]
	ds_read_b128 v[2:5], v215 offset:32768
	ds_read_b128 v[6:9], v215 offset:33792
	ds_read_b128 v[180:183], v215 offset:34816
	ds_read_b128 v[184:187], v215 offset:35840
	ds_read_b128 v[216:219], v215 offset:36864
	ds_read_b128 v[220:223], v215 offset:37888
	ds_read_b128 v[224:227], v215 offset:38912
	ds_read_b128 v[228:231], v215 offset:39936
	global_load_lds_dwordx4 v[208:209], off
	v_lshl_add_u64 v[208:209], v[210:211], 0, s[6:7]
	s_mov_b32 m0, s88
	s_nop 0
	global_load_lds_dwordx4 v[208:209], off
	v_lshl_add_u64 v[208:209], s[12:13], 0, v[192:193]
	s_mov_b32 m0, s89
	s_nop 0
	global_load_lds_dword v[208:209], off
	s_waitcnt vmcnt(9)
	s_waitcnt lgkmcnt(0)
	s_setprio 1
	s_barrier
	v_mfma_f32_16x16x32_bf16 v[134:137], v[146:149], v[2:5], v[134:137]
	v_mfma_f32_16x16x32_bf16 v[130:133], v[154:157], v[2:5], v[130:133]
	v_mfma_f32_16x16x32_bf16 v[126:129], v[146:149], v[180:183], v[126:129]
	v_mfma_f32_16x16x32_bf16 v[122:125], v[154:157], v[180:183], v[122:125]
	v_mfma_f32_16x16x32_bf16 v[114:117], v[146:149], v[216:219], v[114:117]
	v_mfma_f32_16x16x32_bf16 v[106:109], v[154:157], v[216:219], v[106:109]
	v_mfma_f32_16x16x32_bf16 v[98:101], v[146:149], v[224:227], v[98:101]
	v_mfma_f32_16x16x32_bf16 v[90:93], v[154:157], v[224:227], v[90:93]
	v_mfma_f32_16x16x32_bf16 v[134:137], v[150:153], v[6:9], v[134:137]
	v_mfma_f32_16x16x32_bf16 v[130:133], v[158:161], v[6:9], v[130:133]
	v_mfma_f32_16x16x32_bf16 v[126:129], v[150:153], v[184:187], v[126:129]
	v_mfma_f32_16x16x32_bf16 v[122:125], v[158:161], v[184:187], v[122:125]
	v_mfma_f32_16x16x32_bf16 v[114:117], v[150:153], v[220:223], v[114:117]
	v_mfma_f32_16x16x32_bf16 v[106:109], v[158:161], v[220:223], v[106:109]
	v_mfma_f32_16x16x32_bf16 v[98:101], v[150:153], v[228:231], v[98:101]
	v_mfma_f32_16x16x32_bf16 v[90:93], v[158:161], v[228:231], v[90:93]
	s_setprio 0
	s_setprio 1
	v_mfma_f32_16x16x32_bf16 v[118:121], v[166:169], v[2:5], v[118:121]
	v_mfma_f32_16x16x32_bf16 v[2:5], v[174:177], v[2:5], v[110:113]
	v_mfma_f32_16x16x32_bf16 v[110:113], v[162:165], v[6:9], v[2:5]
	v_mfma_f32_16x16x32_bf16 v[2:5], v[166:169], v[180:183], v[102:105]
	v_mfma_f32_16x16x32_bf16 v[102:105], v[170:173], v[184:187], v[2:5]
	v_mfma_f32_16x16x32_bf16 v[2:5], v[174:177], v[180:183], v[94:97]
	v_mfma_f32_16x16x32_bf16 v[94:97], v[162:165], v[184:187], v[2:5]
	v_mfma_f32_16x16x32_bf16 v[2:5], v[166:169], v[216:219], v[86:89]
	v_mfma_f32_16x16x32_bf16 v[86:89], v[170:173], v[220:223], v[2:5]
	v_mfma_f32_16x16x32_bf16 v[2:5], v[174:177], v[216:219], v[82:85]
	v_mfma_f32_16x16x32_bf16 v[82:85], v[162:165], v[220:223], v[2:5]
	v_mfma_f32_16x16x32_bf16 v[2:5], v[166:169], v[224:227], v[78:81]
	v_mfma_f32_16x16x32_bf16 v[78:81], v[170:173], v[228:231], v[2:5]
	v_mfma_f32_16x16x32_bf16 v[2:5], v[174:177], v[224:227], v[74:77]
	v_mfma_f32_16x16x32_bf16 v[118:121], v[170:173], v[6:9], v[118:121]
	v_mfma_f32_16x16x32_bf16 v[74:77], v[162:165], v[228:231], v[2:5]
	s_barrier
; #define PG8_SB(B) __builtin_amdgcn_rcpf(1.f + expneg(B))
; #define PG8_SB(B) __builtin_amdgcn_rcpf(1.f + expneg(B))
; #define PG8_STAGE(bufoff, gbase, voff) do { _Pragma("unroll") for (int _i = 0; _i < 2; ++_i) \
;         __builtin_amdgcn_global_load_lds((const unsigned*)((const char*)(gbase) + (size_t)_i * qstep + (voff)[0]), (PG8_LAS unsigned*)(lds + (bufoff) + ldsw + _i * 8192), 16, 0, 0); } while (0)
; #define PG8_LDA(dst, b, h) do { _Pragma("unroll") for (int m = 0; m < 4; ++m) _Pragma("unroll") for (int k = 0; k < 2; ++k) dst[m][k] = *(const PG8_LAS bf16x8*)(lds + PG8_SA(b, h) + aoff + m * 2048 + k * 1024); } while (0)
; #define PG8_MMA(ai, bj, At, Bt) do { __builtin_amdgcn_s_setprio(1); _Pragma("unroll") for (int m = 0; m < 4; ++m) _Pragma("unroll") for (int n = 0; n < 2; ++n) _Pragma("unroll") for (int k = 0; k < 2; ++k) \
;         acc[ai][bj][m][n] = __builtin_amdgcn_mfma_f32_16x16x32_bf16(Bt[n][k], At[m][k], acc[ai][bj][m][n], 0, 0, 0); __builtin_amdgcn_s_setprio(0); } while (0)
; #define PG8_WAIT_V89() do { if constexpr (SLIVER) PG8_WAIT_V(9); else PG8_WAIT_V(8); } while (0)
; #define PG8_LDS_S(b) do { if constexpr (SLIVER) { Sf[0] = *(const PG8_LAS bf16x8*)(lds + STAGE_BYTES + (b) * 2048 + soff0); Sf[1] = *(const PG8_LAS bf16x8*)(lds + STAGE_BYTES + (b) * 2048 + (soff0 ^ 64)); } } while (0)
; #define PG8_WAIT_L(n) asm volatile("s_waitcnt lgkmcnt(" #n ")" ::: "memory")
; #define PG8_BAR __builtin_amdgcn_s_barrier()
; #define PG8_SCHED __builtin_amdgcn_sched_barrier(0)
; template <class Epi, class Sched, bool ALIGN_EPI = false, bool SP2 = false, bool SLIVER = false>
; __device__ __forceinline__ void gemm_phase(PG8_LAS unsigned char* lds, const Gemm g, const Sched& S, const Epi& E) {
;     ...
;             PG8_LDA(At, 1, 1); PG8_LDS_S(1); PG8_STAGE(PG8_SB(1, 0), b3, voffB); PG8_STAGE(PG8_SB(1, 1), b3 + hstep, voffB); PG8_STAGE(PG8_SA(1, 0), a3, voffA);
;             PG8_WAIT_V89(); PG8_WAIT_L(0); PG8_BAR; PG8_MMA(1, 0, At, B0); PG8_MMA(1, 1, At, B1); PG8_MMA_S(); PG8_BAR; PG8_SCHED;
	s_setprio 0
	s_add_i32 s12, 0, 0x20800
	v_add_u32_e32 v178, s12, v213
	v_add_u32_e32 v184, s12, v214
	s_add_i32 s12, s68, s92
	v_lshl_add_u64 v[208:209], v[202:203], 0, s[26:27]
	s_mov_b32 m0, s12
	ds_read_b128 v[2:5], v215 offset:49152
	ds_read_b128 v[6:9], v215 offset:50176
	ds_read_b128 v[216:219], v215 offset:51200
	ds_read_b128 v[220:223], v215 offset:52224
	ds_read_b128 v[224:227], v215 offset:53248
	ds_read_b128 v[228:231], v215 offset:54272
	ds_read_b128 v[232:235], v215 offset:55296
	ds_read_b128 v[240:243], v215 offset:56320
	ds_read_b128 v[180:183], v178
	ds_read_b128 v[184:187], v184
	global_load_lds_dwordx4 v[208:209], off
	v_lshl_add_u64 v[208:209], v[202:203], 0, s[58:59]
	s_add_i32 m0, s12, 0x2000
	s_mov_b64 s[12:13], 0x90080
	global_load_lds_dwordx4 v[208:209], off
	v_lshl_add_u64 v[208:209], v[202:203], 0, s[12:13]
	s_add_i32 s12, s69, s92
	s_mov_b32 m0, s12
	s_mov_b64 s[68:69], 0xd8080
	global_load_lds_dwordx4 v[208:209], off
	v_lshl_add_u64 v[202:203], v[202:203], 0, s[68:69]
	s_add_i32 m0, s12, 0x2000
	s_nop 0
	global_load_lds_dwordx4 v[202:203], off
	v_lshl_add_u64 v[202:203], v[210:211], 0, s[26:27]
	s_mov_b32 m0, s51
	s_nop 0
	global_load_lds_dwordx4 v[202:203], off
	v_lshl_add_u64 v[202:203], v[210:211], 0, s[58:59]
	s_mov_b32 m0, s53
	s_nop 0
	global_load_lds_dwordx4 v[202:203], off
	s_waitcnt vmcnt(9)
	s_waitcnt lgkmcnt(0)
	s_setprio 1
	s_barrier
	v_mfma_f32_16x16x32_bf16 v[70:73], v[146:149], v[2:5], v[70:73]
	v_mfma_f32_16x16x32_bf16 v[66:69], v[154:157], v[2:5], v[66:69]
	v_mfma_f32_16x16x32_bf16 v[62:65], v[146:149], v[216:219], v[62:65]
	v_mfma_f32_16x16x32_bf16 v[58:61], v[154:157], v[216:219], v[58:61]
	v_mfma_f32_16x16x32_bf16 v[50:53], v[146:149], v[224:227], v[50:53]
	v_mfma_f32_16x16x32_bf16 v[42:45], v[154:157], v[224:227], v[42:45]
	v_mfma_f32_16x16x32_bf16 v[34:37], v[146:149], v[232:235], v[34:37]
	v_mfma_f32_16x16x32_bf16 v[26:29], v[154:157], v[232:235], v[26:29]
	v_mfma_f32_16x16x32_bf16 v[70:73], v[150:153], v[6:9], v[70:73]
	v_mfma_f32_16x16x32_bf16 v[66:69], v[158:161], v[6:9], v[66:69]
	v_mfma_f32_16x16x32_bf16 v[62:65], v[150:153], v[220:223], v[62:65]
	v_mfma_f32_16x16x32_bf16 v[58:61], v[158:161], v[220:223], v[58:61]
	v_mfma_f32_16x16x32_bf16 v[50:53], v[150:153], v[228:231], v[50:53]
	v_mfma_f32_16x16x32_bf16 v[42:45], v[158:161], v[228:231], v[42:45]
	v_mfma_f32_16x16x32_bf16 v[34:37], v[150:153], v[240:243], v[34:37]
	v_mfma_f32_16x16x32_bf16 v[26:29], v[158:161], v[240:243], v[26:29]
	s_setprio 0
	s_setprio 1
	v_mfma_f32_16x16x32_bf16 v[54:57], v[166:169], v[2:5], v[54:57]
	v_mfma_f32_16x16x32_bf16 v[2:5], v[174:177], v[2:5], v[46:49]
	v_mfma_f32_16x16x32_bf16 v[46:49], v[162:165], v[6:9], v[2:5]
	v_mfma_f32_16x16x32_bf16 v[2:5], v[166:169], v[216:219], v[38:41]
	v_mfma_f32_16x16x32_bf16 v[38:41], v[170:173], v[220:223], v[2:5]
	v_mfma_f32_16x16x32_bf16 v[2:5], v[174:177], v[216:219], v[30:33]
	v_mfma_f32_16x16x32_bf16 v[30:33], v[162:165], v[220:223], v[2:5]
	v_mfma_f32_16x16x32_bf16 v[2:5], v[166:169], v[224:227], v[22:25]
	v_mfma_f32_16x16x32_bf16 v[22:25], v[170:173], v[228:231], v[2:5]
	v_mfma_f32_16x16x32_bf16 v[2:5], v[174:177], v[224:227], v[18:21]
	v_mfma_f32_16x16x32_bf16 v[18:21], v[162:165], v[228:231], v[2:5]
	v_mfma_f32_16x16x32_bf16 v[2:5], v[166:169], v[232:235], v[14:17]
	v_mfma_f32_16x16x32_bf16 v[14:17], v[170:173], v[240:243], v[2:5]
	v_mfma_f32_16x16x32_bf16 v[2:5], v[174:177], v[232:235], v[10:13]
	v_mfma_f32_16x16x32_bf16 v[54:57], v[170:173], v[6:9], v[54:57]
	v_mfma_f32_16x16x32_bf16 v[10:13], v[162:165], v[240:243], v[2:5]
	s_setprio 0
	s_setprio 1
	s_and_b64 vcc, exec, s[40:41]
	s_mov_b64 s[12:13], -1
	s_cbranch_vccnz .LBB0_940
	v_mfma_f32_16x16x32_bf16 v[2:5], v[166:169], v[180:183], v[138:141]
	s_mov_b64 s[12:13], 0
	v_mfma_f32_16x16x32_bf16 v[6:9], v[170:173], v[184:187], v[2:5]
	v_mfma_f32_16x16x32_bf16 v[2:5], v[174:177], v[180:183], v[142:145]
	v_mfma_f32_16x16x32_bf16 v[2:5], v[162:165], v[184:187], v[2:5]
